# v9 + P13 residual epilogue also with rolling 4-row-group prefetch
# baseline (speedup 1.0000x reference)
;     __device__ __forceinline__ void operator()(const f32x4 (&acc)[2][2][4][2], const Unit& u, int wr, int wc, int fr, int fq) const {
;         const int row0 = u.pm * BM + wr * 64 + fr, col0 = u.pn * BM + wc * 32 + 4 * fq;
; #pragma unroll
;         for (int ai = 0; ai < 2; ++ai)
; #pragma unroll
;             for (int m = 0; m < 4; ++m) { const int row = row0 + ai * HALF + m * 16;
;                 if (row < nrows) {
;                     const float* bp = (row < split ? base0 + (size_t)row * D : base1 + (size_t)(row - split) * D) + col0; float* op = out + (size_t)row * D + col0;
; #pragma unroll
;                     for (int bj = 0; bj < 2; ++bj)
; #pragma unroll
;                         for (int n = 0; n < 2; ++n) { const f32x4 b = *(const f32x4*)(bp + bj * HALF + n * 16); *(f32x4*)(op + bj * HALF + n * 16) = b + acc[ai][bj][m][n]; } } }
;     }
.LBB0_901:
	v_lshl_or_b32 v140, s57, 8, v146
	v_lshl_add_u32 v142, s56, 8, v144
	v_ashrrev_i32_e32 v141, 31, v140
	v_cmp_gt_i32_e32 vcc, s43, v142
	v_ashrrev_i32_e32 v143, 31, v142
	v_lshlrev_b64 v[140:141], 2, v[140:141]
	s_and_saveexec_b64 s[26:27], vcc
	s_cbranch_execz .LBB0_903
	v_lshlrev_b64 v[154:155], 13, v[142:143]
	v_lshl_add_u64 v[150:151], s[10:11], 0, v[154:155]
	v_lshl_add_u64 v[156:157], v[150:151], 0, v[140:141]
	v_mov_b32_e32 v198, v156
	v_mov_b32_e32 v199, v157
	global_load_dwordx4 v[210:213], v[198:199], off
	global_load_dwordx4 v[214:217], v[198:199], off offset:64
	global_load_dwordx4 v[218:221], v[198:199], off offset:512
	global_load_dwordx4 v[222:225], v[198:199], off offset:576
	s_mov_b32 s100, 0x20000
	s_mov_b32 s101, 0
	v_lshl_add_u64 v[198:199], v[198:199], 0, s[100:101]
	global_load_dwordx4 v[226:229], v[198:199], off
	global_load_dwordx4 v[230:233], v[198:199], off offset:64
	global_load_dwordx4 v[234:237], v[198:199], off offset:512
	global_load_dwordx4 v[238:241], v[198:199], off offset:576
	s_mov_b32 s100, 0x20000
	s_mov_b32 s101, 0
	v_lshl_add_u64 v[198:199], v[198:199], 0, s[100:101]
	global_load_dwordx4 v[242:245], v[198:199], off
	global_load_dwordx4 v[246:249], v[198:199], off offset:64
	global_load_dwordx4 v[250:253], v[198:199], off offset:512
	global_load_dwordx4 v[168:171], v[198:199], off offset:576
	s_mov_b32 s100, 0x20000
	s_mov_b32 s101, 0
	v_lshl_add_u64 v[198:199], v[198:199], 0, s[100:101]
	global_load_dwordx4 v[172:175], v[198:199], off
	global_load_dwordx4 v[176:179], v[198:199], off offset:64
	global_load_dwordx4 v[180:183], v[198:199], off offset:512
	global_load_dwordx4 v[184:187], v[198:199], off offset:576
	v_lshl_add_u64 v[154:155], s[8:9], 0, v[154:155]
	v_lshl_add_u64 v[154:155], v[154:155], 0, v[140:141]
	s_waitcnt vmcnt(15)
	v_pk_add_f32 v[126:127], v[126:127], v[212:213]
	v_pk_add_f32 v[124:125], v[124:125], v[210:211]
	global_store_dwordx4 v[154:155], v[124:127], off
	s_waitcnt vmcnt(15)
	v_pk_add_f32 v[122:123], v[122:123], v[216:217]
	v_pk_add_f32 v[120:121], v[120:121], v[214:215]
	global_store_dwordx4 v[154:155], v[120:123], off offset:64
	s_waitcnt vmcnt(15)
	v_pk_add_f32 v[118:119], v[118:119], v[220:221]
	v_pk_add_f32 v[116:117], v[116:117], v[218:219]
	global_store_dwordx4 v[154:155], v[116:119], off offset:512
	s_waitcnt vmcnt(15)
	v_pk_add_f32 v[114:115], v[114:115], v[224:225]
	v_pk_add_f32 v[112:113], v[112:113], v[222:223]
	global_store_dwordx4 v[154:155], v[112:115], off offset:576
.LBB0_903:
	s_or_b64 exec, exec, s[26:27]
	s_nop 0
	v_or_b32_e32 v112, 16, v142
	v_cmp_gt_i32_e32 vcc, s43, v112
	s_and_saveexec_b64 s[26:27], vcc
	s_cbranch_execz .LBB0_905
	v_ashrrev_i32_e32 v113, 31, v112
	v_lshlrev_b64 v[116:117], 13, v[112:113]
	v_lshl_add_u64 v[112:113], s[10:11], 0, v[116:117]
	v_lshl_add_u64 v[118:119], v[112:113], 0, v[140:141]
	s_mov_b32 s100, 0xa0000
	s_mov_b32 s101, 0
	v_lshl_add_u64 v[198:199], v[198:199], 0, s[100:101]
	global_load_dwordx4 v[210:213], v[198:199], off
	global_load_dwordx4 v[214:217], v[198:199], off offset:64
	global_load_dwordx4 v[218:221], v[198:199], off offset:512
	global_load_dwordx4 v[222:225], v[198:199], off offset:576
	v_lshl_add_u64 v[116:117], s[8:9], 0, v[116:117]
	v_lshl_add_u64 v[116:117], v[116:117], 0, v[140:141]
	s_waitcnt vmcnt(19)
	v_pk_add_f32 v[110:111], v[110:111], v[228:229]
	v_pk_add_f32 v[108:109], v[108:109], v[226:227]
	global_store_dwordx4 v[116:117], v[108:111], off
	s_waitcnt vmcnt(19)
	v_pk_add_f32 v[106:107], v[106:107], v[232:233]
	v_pk_add_f32 v[104:105], v[104:105], v[230:231]
	global_store_dwordx4 v[116:117], v[104:107], off offset:64
	s_waitcnt vmcnt(19)
	v_pk_add_f32 v[102:103], v[102:103], v[236:237]
	v_pk_add_f32 v[100:101], v[100:101], v[234:235]
	global_store_dwordx4 v[116:117], v[100:103], off offset:512
	s_waitcnt vmcnt(19)
	v_pk_add_f32 v[98:99], v[98:99], v[240:241]
	v_pk_add_f32 v[96:97], v[96:97], v[238:239]
	global_store_dwordx4 v[116:117], v[96:99], off offset:576
.LBB0_905:
	s_or_b64 exec, exec, s[26:27]
	s_nop 0
	v_or_b32_e32 v96, 32, v142
	v_cmp_gt_i32_e32 vcc, s43, v96
	s_and_saveexec_b64 s[26:27], vcc
	s_cbranch_execz .LBB0_907
	v_ashrrev_i32_e32 v97, 31, v96
	v_lshlrev_b64 v[100:101], 13, v[96:97]
	v_lshl_add_u64 v[96:97], s[10:11], 0, v[100:101]
	v_lshl_add_u64 v[102:103], v[96:97], 0, v[140:141]
	s_mov_b32 s100, 0x20000
	s_mov_b32 s101, 0
	v_lshl_add_u64 v[198:199], v[198:199], 0, s[100:101]
	global_load_dwordx4 v[226:229], v[198:199], off
	global_load_dwordx4 v[230:233], v[198:199], off offset:64
	global_load_dwordx4 v[234:237], v[198:199], off offset:512
	global_load_dwordx4 v[238:241], v[198:199], off offset:576
	v_lshl_add_u64 v[100:101], s[8:9], 0, v[100:101]
	v_lshl_add_u64 v[100:101], v[100:101], 0, v[140:141]
	s_waitcnt vmcnt(23)
	v_pk_add_f32 v[94:95], v[94:95], v[244:245]
	v_pk_add_f32 v[92:93], v[92:93], v[242:243]
	global_store_dwordx4 v[100:101], v[92:95], off
	s_waitcnt vmcnt(23)
	v_pk_add_f32 v[90:91], v[90:91], v[248:249]
	v_pk_add_f32 v[88:89], v[88:89], v[246:247]
	global_store_dwordx4 v[100:101], v[88:91], off offset:64
	s_waitcnt vmcnt(23)
	v_pk_add_f32 v[86:87], v[86:87], v[252:253]
	v_pk_add_f32 v[84:85], v[84:85], v[250:251]
	global_store_dwordx4 v[100:101], v[84:87], off offset:512
	s_waitcnt vmcnt(23)
	v_pk_add_f32 v[82:83], v[82:83], v[170:171]
	v_pk_add_f32 v[80:81], v[80:81], v[168:169]
	global_store_dwordx4 v[100:101], v[80:83], off offset:576

;     __device__ __forceinline__ void operator()(const f32x4 (&acc)[2][2][4][2], const Unit& u, int wr, int wc, int fr, int fq) const {
;         const int row0 = u.pm * BM + wr * 64 + fr, col0 = u.pn * BM + wc * 32 + 4 * fq;
; #pragma unroll
;         for (int ai = 0; ai < 2; ++ai)
; #pragma unroll
;             for (int m = 0; m < 4; ++m) { const int row = row0 + ai * HALF + m * 16;
;                 if (row < nrows) {
;                     const float* bp = (row < split ? base0 + (size_t)row * D : base1 + (size_t)(row - split) * D) + col0; float* op = out + (size_t)row * D + col0;
; #pragma unroll
;                     for (int bj = 0; bj < 2; ++bj)
; #pragma unroll
;                         for (int n = 0; n < 2; ++n) { const f32x4 b = *(const f32x4*)(bp + bj * HALF + n * 16); *(f32x4*)(op + bj * HALF + n * 16) = b + acc[ai][bj][m][n]; } } }
;     }
.LBB0_913:
	v_ashrrev_i32_e32 v81, 31, v80
	v_lshlrev_b64 v[84:85], 13, v[80:81]
	v_lshl_add_u64 v[80:81], s[10:11], 0, v[84:85]
	v_lshl_add_u64 v[86:87], v[80:81], 0, v[140:141]
	s_mov_b32 s100, 0x20000
	s_mov_b32 s101, 0
	v_lshl_add_u64 v[198:199], v[198:199], 0, s[100:101]
	global_load_dwordx4 v[242:245], v[198:199], off
	global_load_dwordx4 v[246:249], v[198:199], off offset:64
	global_load_dwordx4 v[250:253], v[198:199], off offset:512
	global_load_dwordx4 v[168:171], v[198:199], off offset:576
	v_lshl_add_u64 v[84:85], s[8:9], 0, v[84:85]
	v_lshl_add_u64 v[84:85], v[84:85], 0, v[140:141]
	s_waitcnt vmcnt(27)
	v_pk_add_f32 v[78:79], v[78:79], v[174:175]
	v_pk_add_f32 v[76:77], v[76:77], v[172:173]
	global_store_dwordx4 v[84:85], v[76:79], off
	s_waitcnt vmcnt(27)
	v_pk_add_f32 v[74:75], v[74:75], v[178:179]
	v_pk_add_f32 v[72:73], v[72:73], v[176:177]
	global_store_dwordx4 v[84:85], v[72:75], off offset:64
	s_waitcnt vmcnt(27)
	v_pk_add_f32 v[70:71], v[70:71], v[182:183]
	v_pk_add_f32 v[68:69], v[68:69], v[180:181]
	global_store_dwordx4 v[84:85], v[68:71], off offset:512
	s_waitcnt vmcnt(27)
	v_pk_add_f32 v[66:67], v[66:67], v[186:187]
	v_pk_add_f32 v[64:65], v[64:65], v[184:185]
	global_store_dwordx4 v[84:85], v[64:67], off offset:576
	s_or_b64 exec, exec, s[26:27]
	v_cmp_gt_i32_e32 vcc, s50, v142
	s_and_saveexec_b64 s[26:27], vcc
	s_cbranch_execz .LBB0_909
.LBB0_914:
	v_lshlrev_b64 v[64:65], 13, v[142:143]
	v_lshl_add_u64 v[68:69], v[64:65], 0, s[18:19]
	v_lshl_add_u64 v[64:65], s[10:11], 0, v[68:69]
	v_lshl_add_u64 v[70:71], v[64:65], 0, v[140:141]
	s_mov_b32 s100, 0x20000
	s_mov_b32 s101, 0
	v_lshl_add_u64 v[198:199], v[198:199], 0, s[100:101]
	global_load_dwordx4 v[172:175], v[198:199], off
	global_load_dwordx4 v[176:179], v[198:199], off offset:64
	global_load_dwordx4 v[180:183], v[198:199], off offset:512
	global_load_dwordx4 v[184:187], v[198:199], off offset:576
	v_lshl_add_u64 v[68:69], s[8:9], 0, v[68:69]
	v_lshl_add_u64 v[68:69], v[68:69], 0, v[140:141]
	s_waitcnt vmcnt(27)
	v_pk_add_f32 v[62:63], v[62:63], v[212:213]
	v_pk_add_f32 v[60:61], v[60:61], v[210:211]
	global_store_dwordx4 v[68:69], v[60:63], off
	s_waitcnt vmcnt(27)
	v_pk_add_f32 v[58:59], v[58:59], v[216:217]
	v_pk_add_f32 v[56:57], v[56:57], v[214:215]
	global_store_dwordx4 v[68:69], v[56:59], off offset:64
	s_waitcnt vmcnt(27)
	v_pk_add_f32 v[54:55], v[54:55], v[220:221]
	v_pk_add_f32 v[52:53], v[52:53], v[218:219]
	global_store_dwordx4 v[68:69], v[52:55], off offset:512
	s_waitcnt vmcnt(27)
	v_pk_add_f32 v[50:51], v[50:51], v[224:225]
	v_pk_add_f32 v[48:49], v[48:49], v[222:223]
	global_store_dwordx4 v[68:69], v[48:51], off offset:576
	s_or_b64 exec, exec, s[26:27]
	v_cmp_gt_i32_e32 vcc, s51, v142
	s_and_saveexec_b64 s[26:27], vcc
	s_cbranch_execz .LBB0_910
.LBB0_915:
	v_lshlrev_b64 v[48:49], 13, v[142:143]
	v_lshl_add_u64 v[52:53], v[48:49], 0, s[20:21]
	v_lshl_add_u64 v[48:49], s[10:11], 0, v[52:53]
	v_lshl_add_u64 v[54:55], v[48:49], 0, v[140:141]
	v_lshl_add_u64 v[52:53], s[8:9], 0, v[52:53]
	v_lshl_add_u64 v[52:53], v[52:53], 0, v[140:141]
	s_waitcnt vmcnt(23)
	v_pk_add_f32 v[46:47], v[46:47], v[228:229]
	v_pk_add_f32 v[44:45], v[44:45], v[226:227]
	global_store_dwordx4 v[52:53], v[44:47], off
	s_waitcnt vmcnt(23)
	v_pk_add_f32 v[42:43], v[42:43], v[232:233]
	v_pk_add_f32 v[40:41], v[40:41], v[230:231]
	global_store_dwordx4 v[52:53], v[40:43], off offset:64
	s_waitcnt vmcnt(23)
	v_pk_add_f32 v[38:39], v[38:39], v[236:237]
	v_pk_add_f32 v[36:37], v[36:37], v[234:235]
	global_store_dwordx4 v[52:53], v[36:39], off offset:512
	s_waitcnt vmcnt(23)
	v_pk_add_f32 v[34:35], v[34:35], v[240:241]
	v_pk_add_f32 v[32:33], v[32:33], v[238:239]
	global_store_dwordx4 v[52:53], v[32:35], off offset:576
	s_or_b64 exec, exec, s[26:27]
	v_cmp_gt_i32_e32 vcc, s52, v142
	s_and_saveexec_b64 s[26:27], vcc
	s_cbranch_execz .LBB0_911
.LBB0_916:
	v_lshlrev_b64 v[32:33], 13, v[142:143]
	v_lshl_add_u64 v[36:37], v[32:33], 0, s[22:23]
	v_lshl_add_u64 v[32:33], s[10:11], 0, v[36:37]
	v_lshl_add_u64 v[38:39], v[32:33], 0, v[140:141]
	v_lshl_add_u64 v[36:37], s[8:9], 0, v[36:37]
	v_lshl_add_u64 v[36:37], v[36:37], 0, v[140:141]
	s_waitcnt vmcnt(19)
	v_pk_add_f32 v[30:31], v[30:31], v[244:245]
	v_pk_add_f32 v[28:29], v[28:29], v[242:243]
	global_store_dwordx4 v[36:37], v[28:31], off
	s_waitcnt vmcnt(19)
	v_pk_add_f32 v[26:27], v[26:27], v[248:249]
	v_pk_add_f32 v[24:25], v[24:25], v[246:247]
	global_store_dwordx4 v[36:37], v[24:27], off offset:64
	s_waitcnt vmcnt(19)
	v_pk_add_f32 v[22:23], v[22:23], v[252:253]
	v_pk_add_f32 v[20:21], v[20:21], v[250:251]
	global_store_dwordx4 v[36:37], v[20:23], off offset:512
	s_waitcnt vmcnt(19)
	v_pk_add_f32 v[18:19], v[18:19], v[170:171]
	v_pk_add_f32 v[16:17], v[16:17], v[168:169]
	global_store_dwordx4 v[36:37], v[16:19], off offset:576
	s_or_b64 exec, exec, s[26:27]
	v_cmp_gt_i32_e32 vcc, s53, v142
	s_and_saveexec_b64 s[26:27], vcc
	s_cbranch_execz .LBB0_912
.LBB0_917:
	v_lshlrev_b64 v[16:17], 13, v[142:143]
	v_lshl_add_u64 v[20:21], v[16:17], 0, s[6:7]
	v_lshl_add_u64 v[16:17], s[10:11], 0, v[20:21]
	v_lshl_add_u64 v[22:23], v[16:17], 0, v[140:141]
	v_lshl_add_u64 v[20:21], s[8:9], 0, v[20:21]
	v_lshl_add_u64 v[20:21], v[20:21], 0, v[140:141]
	s_waitcnt vmcnt(15)
	v_pk_add_f32 v[14:15], v[14:15], v[174:175]
	v_pk_add_f32 v[12:13], v[12:13], v[172:173]
	global_store_dwordx4 v[20:21], v[12:15], off
	s_waitcnt vmcnt(15)
	v_pk_add_f32 v[10:11], v[10:11], v[178:179]
	v_pk_add_f32 v[8:9], v[8:9], v[176:177]
	global_store_dwordx4 v[20:21], v[8:11], off offset:64
	s_waitcnt vmcnt(15)
	v_pk_add_f32 v[6:7], v[6:7], v[182:183]
	v_pk_add_f32 v[4:5], v[4:5], v[180:181]
	global_store_dwordx4 v[20:21], v[4:7], off offset:512
	s_waitcnt vmcnt(15)
	v_pk_add_f32 v[2:3], v[2:3], v[186:187]
	v_pk_add_f32 v[0:1], v[0:1], v[184:185]
	global_store_dwordx4 v[20:21], v[0:3], off offset:576
	s_or_b64 exec, exec, s[26:27]
	s_and_b64 vcc, exec, s[0:1]
	s_mov_b64 s[0:1], -1
	s_cbranch_vccnz .LBB0_886
